# speedup vs baseline: 1.0007x; 1.0007x over previous
.LBB0_183:
	s_or_b64 exec, exec, s[6:7]
	s_bfe_u32 s3, s2, 0x20004
	s_and_b32 s18, s2, 15
	v_mov_b32_e32 v143, v131
	s_not_b32 s2, s2
	s_lshl_b32 s2, s2, 2
	v_ashrrev_i32_e32 v32, 6, v143
	s_lshl_b32 s6, s3, 13
	s_and_b32 s2, s2, 0x1f00
	v_lshlrev_b32_e32 v0, 5, v32
	s_or_b32 s34, s6, s2
	v_ashrrev_i32_e32 v1, 31, v0
	v_lshl_add_u64 v[132:133], s[34:35], 0, v[0:1]
	v_lshlrev_b64 v[2:3], 11, v[132:133]
	v_and_b32_e32 v148, 31, v143
	v_lshl_add_u64 v[2:3], s[12:13], 0, v[2:3]
	s_lshl_b32 s34, s18, 7
	v_bfe_u32 v146, v143, 5, 1
	v_lshl_add_u64 v[2:3], v[2:3], 0, s[34:35]
	v_lshlrev_b32_e32 v128, 11, v148
	v_lshl_add_u64 v[2:3], v[2:3], 0, v[128:129]
	v_lshlrev_b32_e32 v128, 4, v146
	v_lshl_add_u64 v[14:15], v[2:3], 0, v[128:129]
	global_load_dwordx4 v[2:5], v[14:15], off nt
	global_load_dwordx4 v[6:9], v[14:15], off offset:32 nt
	global_load_dwordx4 v[10:13], v[14:15], off offset:64 nt
	s_nop 0
	global_load_dwordx4 v[14:17], v[14:15], off offset:96 nt
	v_and_b32_e32 v1, 32, v143
	global_load_dwordx4 v[18:21], v1, s[68:69] offset:16
	global_load_dwordx4 v[22:25], v1, s[68:69]
	global_load_dwordx4 v[206:209], v1, s[68:69] offset:64
	global_load_dwordx4 v[210:213], v1, s[68:69] offset:80
	global_load_dwordx4 v[214:217], v1, s[68:69] offset:128
	global_load_dwordx4 v[218:221], v1, s[68:69] offset:144
	global_load_dwordx4 v[222:225], v1, s[68:69] offset:192
	global_load_dwordx4 v[226:229], v1, s[68:69] offset:208
	s_lshl_b32 s6, s3, 19
	s_add_u32 s6, s76, s6
	s_addc_u32 s7, s71, 0
	s_lshl_b32 s8, s18, 15
	s_add_u32 s38, s6, s8
	s_addc_u32 s39, s7, 0
	s_lshl_b32 s6, s2, 2
	v_and_b32_e32 v144, 63, v143
	s_mov_b64 s[8:9], 0
	s_waitcnt vmcnt(11)
	v_and_b32_e32 v27, 0xffff0000, v2
	v_lshlrev_b32_e32 v26, 16, v2
	s_waitcnt vmcnt(10)
	v_lshlrev_b32_e32 v39, 16, v8
	v_and_b32_e32 v40, 0xffff0000, v8
	v_mul_f32_e32 v8, v27, v27
	v_lshlrev_b32_e32 v28, 16, v3
	v_fmac_f32_e32 v8, v26, v26
	v_and_b32_e32 v29, 0xffff0000, v3
	v_fmac_f32_e32 v8, v28, v28
	v_lshlrev_b32_e32 v30, 16, v4
	v_fmac_f32_e32 v8, v29, v29
	v_and_b32_e32 v31, 0xffff0000, v4
	v_fmac_f32_e32 v8, v30, v30
	v_lshlrev_b32_e32 v33, 16, v5
	v_fmac_f32_e32 v8, v31, v31
	v_and_b32_e32 v34, 0xffff0000, v5
	v_fmac_f32_e32 v8, v33, v33
	v_lshlrev_b32_e32 v35, 16, v6
	v_fmac_f32_e32 v8, v34, v34
	v_and_b32_e32 v36, 0xffff0000, v6
	v_fmac_f32_e32 v8, v35, v35
	v_lshlrev_b32_e32 v37, 16, v7
	v_fmac_f32_e32 v8, v36, v36
	v_and_b32_e32 v38, 0xffff0000, v7
	v_fmac_f32_e32 v8, v37, v37
	v_fmac_f32_e32 v8, v38, v38
	v_fmac_f32_e32 v8, v39, v39
	v_lshlrev_b32_e32 v41, 16, v9
	v_fmac_f32_e32 v8, v40, v40
	v_and_b32_e32 v42, 0xffff0000, v9
	v_fmac_f32_e32 v8, v41, v41
	s_waitcnt vmcnt(9)
	v_lshlrev_b32_e32 v43, 16, v10
	v_fmac_f32_e32 v8, v42, v42
	v_and_b32_e32 v44, 0xffff0000, v10
	v_fmac_f32_e32 v8, v43, v43
	v_lshlrev_b32_e32 v45, 16, v11
	v_fmac_f32_e32 v8, v44, v44
	v_and_b32_e32 v46, 0xffff0000, v11
	v_fmac_f32_e32 v8, v45, v45
	v_lshlrev_b32_e32 v47, 16, v12
	v_fmac_f32_e32 v8, v46, v46
	v_and_b32_e32 v48, 0xffff0000, v12
	v_fmac_f32_e32 v8, v47, v47
	v_lshlrev_b32_e32 v49, 16, v13
	v_fmac_f32_e32 v8, v48, v48
	v_and_b32_e32 v50, 0xffff0000, v13
	v_fmac_f32_e32 v8, v49, v49
	s_waitcnt vmcnt(8)
	v_lshlrev_b32_e32 v51, 16, v14
	v_fmac_f32_e32 v8, v50, v50
	v_and_b32_e32 v52, 0xffff0000, v14
	v_and_b32_e32 v10, 0xffff0000, v15
	v_lshlrev_b32_e32 v11, 16, v15
	v_fmac_f32_e32 v8, v51, v51
	v_pk_mul_f32 v[2:3], v[10:11], v[10:11]
	v_fmac_f32_e32 v8, v52, v52
	v_and_b32_e32 v12, 0xffff0000, v16
	v_lshlrev_b32_e32 v13, 16, v16
	v_add_f32_e32 v3, v3, v8
	v_pk_mul_f32 v[4:5], v[12:13], v[12:13]
	v_add_f32_e32 v2, v2, v3
	v_and_b32_e32 v14, 0xffff0000, v17
	v_lshlrev_b32_e32 v15, 16, v17
	v_add_f32_e32 v2, v5, v2
	v_pk_mul_f32 v[6:7], v[14:15], v[14:15]
	v_add_f32_e32 v2, v4, v2
	v_add_f32_e32 v2, v7, v2
	v_add_f32_e32 v2, v6, v2
	v_mov_b32_e32 v3, v2
	s_nop 1
	v_permlane32_swap_b32_e32 v2, v3
	v_add_f32_e32 v2, v2, v3
	v_fmamk_f32 v2, v2, 0x3c800000, v130
	v_mul_f32_e32 v3, 0x4b800000, v2
	v_cmp_gt_f32_e32 vcc, s89, v2
	s_nop 1
	v_cndmask_b32_e32 v2, v2, v3, vcc
	v_rsq_f32_e32 v2, v2
	s_nop 0
	v_mul_f32_e32 v3, 0x45800000, v2
	v_cndmask_b32_e32 v16, v2, v3, vcc
	v_mul_f32_e32 v2, v16, v26
	v_mul_f32_e32 v3, v16, v27
	v_mul_f32_e32 v4, v16, v28
	v_mul_f32_e32 v5, v16, v29
	v_mul_f32_e32 v6, v16, v30
	v_mul_f32_e32 v7, v16, v31
	v_mul_f32_e32 v8, v16, v33
	v_mul_f32_e32 v9, v16, v34
	s_waitcnt vmcnt(6)
	v_mul_f32_e32 v2, v22, v2
	v_mul_f32_e32 v3, v23, v3
	v_mul_f32_e32 v4, v24, v4
	v_mul_f32_e32 v5, v25, v5
	v_mul_f32_e32 v6, v18, v6
	v_mul_f32_e32 v7, v19, v7
	v_mul_f32_e32 v8, v20, v8
	v_mul_f32_e32 v9, v21, v9
	v_cvt_pk_bf16_f32 v96, v2, v3
	v_cvt_pk_bf16_f32 v97, v4, v5
	v_cvt_pk_bf16_f32 v98, v6, v7
	v_cvt_pk_bf16_f32 v99, v8, v9
	s_waitcnt vmcnt(4)
	v_mov_b32_e32 v2, v206
	v_mov_b32_e32 v3, v207
	v_mov_b32_e32 v4, v208
	v_mov_b32_e32 v5, v209
	v_mov_b32_e32 v6, v210
	v_mov_b32_e32 v7, v211
	v_mov_b32_e32 v8, v212
	v_mov_b32_e32 v9, v213
	v_mul_f32_e32 v17, v16, v35
	v_mul_f32_e32 v18, v16, v36
	v_mul_f32_e32 v19, v16, v37
	v_mul_f32_e32 v20, v16, v38
	v_mul_f32_e32 v21, v16, v39
	v_mul_f32_e32 v22, v16, v40
	v_mul_f32_e32 v23, v16, v41
	v_mul_f32_e32 v24, v16, v42
	v_mul_f32_e32 v11, v16, v11
	v_mul_f32_e32 v10, v16, v10
	v_mul_f32_e32 v13, v16, v13
	v_mul_f32_e32 v12, v16, v12
	v_mul_f32_e32 v15, v16, v15
	v_mul_f32_e32 v14, v16, v14
	s_waitcnt vmcnt(1)
	v_mul_f32_e32 v2, v2, v17
	v_mul_f32_e32 v3, v3, v18
	v_mul_f32_e32 v4, v4, v19
	v_mul_f32_e32 v5, v5, v20
	s_waitcnt vmcnt(0)
	v_mul_f32_e32 v6, v6, v21
	v_mul_f32_e32 v7, v7, v22
	v_mul_f32_e32 v8, v8, v23
	v_mul_f32_e32 v9, v9, v24
	v_cvt_pk_bf16_f32 v100, v2, v3
	v_cvt_pk_bf16_f32 v101, v4, v5
	v_cvt_pk_bf16_f32 v102, v6, v7
	v_cvt_pk_bf16_f32 v103, v8, v9
	s_waitcnt vmcnt(2)
	v_mov_b32_e32 v2, v214
	v_mov_b32_e32 v3, v215
	v_mov_b32_e32 v4, v216
	v_mov_b32_e32 v5, v217
	v_mov_b32_e32 v6, v218
	v_mov_b32_e32 v7, v219
	v_mov_b32_e32 v8, v220
	v_mov_b32_e32 v9, v221
	v_mul_f32_e32 v17, v16, v43
	v_mul_f32_e32 v18, v16, v44
	v_mul_f32_e32 v19, v16, v45
	v_mul_f32_e32 v20, v16, v46
	v_mul_f32_e32 v21, v16, v47
	v_mul_f32_e32 v22, v16, v48
	v_mul_f32_e32 v23, v16, v49
	v_mul_f32_e32 v24, v16, v50
	s_waitcnt vmcnt(1)
	v_mul_f32_e32 v2, v17, v2
	v_mul_f32_e32 v3, v18, v3
	v_mul_f32_e32 v4, v19, v4
	v_mul_f32_e32 v5, v20, v5
	s_waitcnt vmcnt(0)
	v_mul_f32_e32 v6, v21, v6
	v_mul_f32_e32 v7, v22, v7
	v_mul_f32_e32 v8, v23, v8
	v_mul_f32_e32 v9, v24, v9
	v_cvt_pk_bf16_f32 v104, v2, v3
	v_cvt_pk_bf16_f32 v105, v4, v5
	v_cvt_pk_bf16_f32 v106, v6, v7
	v_cvt_pk_bf16_f32 v107, v8, v9
	s_waitcnt vmcnt(0)
	v_mov_b32_e32 v2, v222
	v_mov_b32_e32 v3, v223
	v_mov_b32_e32 v4, v224
	v_mov_b32_e32 v5, v225
	v_mov_b32_e32 v6, v226
	v_mov_b32_e32 v7, v227
	v_mov_b32_e32 v8, v228
	v_mov_b32_e32 v9, v229
	v_mov_b32_e32 v1, s6
	v_mul_f32_e32 v17, v16, v51
	v_mul_f32_e32 v18, v16, v52
	s_add_i32 s6, s2, 0x100
	s_lshr_b32 s77, s6, 6
	v_cmp_gt_u32_e32 vcc, s77, v144
	s_mov_b64 s[6:7], 0
	s_waitcnt vmcnt(1)
	v_mul_f32_e32 v2, v17, v2
	v_mul_f32_e32 v3, v18, v3
	v_mul_f32_e32 v4, v11, v4
	v_mul_f32_e32 v5, v10, v5
	s_waitcnt vmcnt(0)
	v_mul_f32_e32 v6, v13, v6
	v_mul_f32_e32 v7, v12, v7
	v_mul_f32_e32 v8, v15, v8
	v_mul_f32_e32 v9, v14, v9
	v_cvt_pk_bf16_f32 v108, v2, v3
	v_cvt_pk_bf16_f32 v109, v4, v5
	v_cvt_pk_bf16_f32 v110, v6, v7
	v_cvt_pk_bf16_f32 v111, v8, v9
	global_load_dword v1, v1, s[38:39]
	v_or_b32_e32 v245, 64, v144
	v_lshlrev_b32_e32 v245, 8, v245
	global_load_dword v244, v245, s[38:39] offset:252
	s_and_saveexec_b64 s[10:11], vcc
	s_cbranch_execz .LBB0_185
	v_lshlrev_b32_e32 v2, 8, v144
	global_load_dword v2, v2, s[38:39] offset:252
	s_waitcnt vmcnt(0)
	v_sub_f32_e32 v2, v2, v1
	v_mul_f32_e32 v2, 0x3e000000, v2
	v_cmp_lt_f32_e64 s[8:9], v2, -v142
	s_and_b64 s[8:9], s[8:9], exec
.LBB0_185:
	s_or_b64 exec, exec, s[10:11]
	v_or_b32_e32 v2, 64, v144
	v_cmp_gt_u32_e32 vcc, s77, v2
	s_and_saveexec_b64 s[10:11], vcc
	s_cbranch_execz .LBB0_187
	s_waitcnt vmcnt(0)
	v_mov_b32_e32 v2, v244
	v_sub_f32_e32 v1, v2, v1
	v_mul_f32_e32 v1, 0x3e000000, v1
	v_cmp_lt_f32_e64 s[6:7], v1, -v142
	s_and_b64 s[6:7], s[6:7], exec
